# gMLP epilogue: 8 serialized gain-vector loads (each followed by vmcnt(0) that also waited on the previous store) hoisted ahead of the MFMA section
# speedup vs baseline: 1.0010x; 1.0010x over previous
; __device__ __forceinline__ unsigned cvt_pk(float lo, float hi) { unsigned r; asm volatile("v_cvt_pk_bf16_f32 %0, %1, %2" : "=v"(r) : "v"(lo), "v"(hi)); return r; }
; __device__ __forceinline__ void gmlp_phase(const Params& p, LAS unsigned char* lds, int G) {
;     ...
;             const int i = 32 * wi + l32; const size_t tok = (size_t)(row0 + i);
;             const int cb = g * 128 + 64 * wc + 4 * hi;
;             const bf16_t* ap = WSM + (size_t)(g * 128 + i) * 128 + 8 * hi;
;             bf16x8 wf[8]; u32x2 guv[8];
; #pragma unroll
;             for (int ks = 0; ks < 8; ++ks) wf[ks] = *(const bf16x8*)(ap + 16 * ks);
; #pragma unroll
;             for (int q = 0; q < 4; ++q) { guv[2 * q] = *(const u32x2*)(GU + tok * 512 + cb + 8 * q); guv[2 * q + 1] = *(const u32x2*)(GU + tok * 512 + cb + 32 + 8 * q); }
;             const float bi = bs[g * 128 + i];
;             {
;                 float f[32];
;                 f[0] = bflo(v0.x); f[1] = bfhi(v0.x); f[2] = bflo(v0.y); f[3] = bfhi(v0.y); f[4] = bflo(v0.z); f[5] = bfhi(v0.z); f[6] = bflo(v0.w); f[7] = bfhi(v0.w);
;                 f[8] = bflo(v1.x); f[9] = bfhi(v1.x); f[10] = bflo(v1.y); f[11] = bfhi(v1.y); f[12] = bflo(v1.z); f[13] = bfhi(v1.z); f[14] = bflo(v1.w); f[15] = bfhi(v1.w);
;                 f[16] = bflo(v2.x); f[17] = bfhi(v2.x); f[18] = bflo(v2.y); f[19] = bfhi(v2.y); f[20] = bflo(v2.z); f[21] = bfhi(v2.z); f[22] = bflo(v2.w); f[23] = bfhi(v2.w);
;                 f[24] = bflo(v3.x); f[25] = bfhi(v3.x); f[26] = bflo(v3.y); f[27] = bfhi(v3.y); f[28] = bflo(v3.z); f[29] = bfhi(v3.z); f[30] = bflo(v3.w); f[31] = bfhi(v3.w);
;                 float ss = 0.f;
; #pragma unroll
;                 for (int e = 0; e < 32; ++e) ss += f[e] * f[e];
;                 ss += __shfl_xor(ss, 1); ss += __shfl_xor(ss, 2);
;                 const float r = 1.0f / sqrtf(ss * (1.f / 128.f) + EPS);
; #pragma unroll
;                 for (int e = 0; e < 32; e += 2) { const unsigned w = cvt_pk(f[e] * r, f[e + 1] * r);
;                     vT[(part * 32 + e) * 136 + j] = (bf16_t)(w & 0xffffu); vT[(part * 32 + e + 1) * 136 + j] = (bf16_t)(w >> 16); }
.LBB0_654:
	s_waitcnt vmcnt(0)
	v_and_b32_e32 v7, 0xffff0000, v44
	v_lshlrev_b32_e32 v6, 16, v44
	v_lshlrev_b32_e32 v26, 16, v38
	v_and_b32_e32 v27, 0xffff0000, v38
	v_mul_f32_e32 v38, v7, v7
	v_lshlrev_b32_e32 v8, 16, v45
	v_fmac_f32_e32 v38, v6, v6
	v_and_b32_e32 v9, 0xffff0000, v45
	v_fmac_f32_e32 v38, v8, v8
	v_lshlrev_b32_e32 v10, 16, v46
	v_fmac_f32_e32 v38, v9, v9
	v_and_b32_e32 v11, 0xffff0000, v46
	v_fmac_f32_e32 v38, v10, v10
	v_lshlrev_b32_e32 v12, 16, v47
	v_fmac_f32_e32 v38, v11, v11
	v_and_b32_e32 v13, 0xffff0000, v47
	v_fmac_f32_e32 v38, v12, v12
	v_lshlrev_b32_e32 v14, 16, v40
	v_fmac_f32_e32 v38, v13, v13
	v_and_b32_e32 v15, 0xffff0000, v40
	v_fmac_f32_e32 v38, v14, v14
	v_lshlrev_b32_e32 v16, 16, v41
	v_fmac_f32_e32 v38, v15, v15
	v_and_b32_e32 v17, 0xffff0000, v41
	v_fmac_f32_e32 v38, v16, v16
	v_lshlrev_b32_e32 v18, 16, v42
	v_fmac_f32_e32 v38, v17, v17
	v_and_b32_e32 v19, 0xffff0000, v42
	v_fmac_f32_e32 v38, v18, v18
	v_lshlrev_b32_e32 v20, 16, v43
	v_fmac_f32_e32 v38, v19, v19
	v_and_b32_e32 v21, 0xffff0000, v43
	v_fmac_f32_e32 v38, v20, v20
	v_lshlrev_b32_e32 v22, 16, v36
	v_fmac_f32_e32 v38, v21, v21
	v_and_b32_e32 v23, 0xffff0000, v36
	v_fmac_f32_e32 v38, v22, v22
	v_lshlrev_b32_e32 v24, 16, v37
	v_fmac_f32_e32 v38, v23, v23
	v_and_b32_e32 v25, 0xffff0000, v37
	v_fmac_f32_e32 v38, v24, v24
	v_fmac_f32_e32 v38, v25, v25
	v_fmac_f32_e32 v38, v26, v26
	v_lshlrev_b32_e32 v28, 16, v39
	v_fmac_f32_e32 v38, v27, v27
	v_and_b32_e32 v29, 0xffff0000, v39
	v_fmac_f32_e32 v38, v28, v28
	v_lshlrev_b32_e32 v30, 16, v32
	v_fmac_f32_e32 v38, v29, v29
	v_and_b32_e32 v31, 0xffff0000, v32
	v_fmac_f32_e32 v38, v30, v30
	v_lshlrev_b32_e32 v32, 16, v33
	v_fmac_f32_e32 v38, v31, v31
	v_and_b32_e32 v33, 0xffff0000, v33
	v_fmac_f32_e32 v38, v32, v32
	v_lshlrev_b32_e32 v36, 16, v34
	v_fmac_f32_e32 v38, v33, v33
	v_and_b32_e32 v34, 0xffff0000, v34
	v_fmac_f32_e32 v38, v36, v36
	v_lshlrev_b32_e32 v37, 16, v35
	v_fmac_f32_e32 v38, v34, v34
	v_and_b32_e32 v35, 0xffff0000, v35
	v_fmac_f32_e32 v38, v37, v37
	v_fmac_f32_e32 v38, v35, v35
	ds_bpermute_b32 v39, v167, v38
	v_ashrrev_i32_e32 v113, 31, v112
	v_lshlrev_b64 v[0:1], 8, v[112:113]
	v_lshl_add_u64 v[4:5], v[82:83], 0, v[0:1]
	global_load_dwordx4 v[0:3], v[4:5], off
	global_load_dwordx4 v[72:75], v[4:5], off offset:32
	global_load_dwordx4 v[68:71], v[4:5], off offset:64
	global_load_dwordx4 v[64:67], v[4:5], off offset:96
	global_load_dwordx4 v[60:63], v[4:5], off offset:128
	global_load_dwordx4 v[56:59], v[4:5], off offset:160
	global_load_dwordx4 v[52:55], v[4:5], off offset:192
	global_load_dwordx4 v[48:51], v[4:5], off offset:224
	s_waitcnt lgkmcnt(0)
	v_add_f32_e32 v38, v38, v39
	ds_bpermute_b32 v39, v168, v38
	v_lshl_add_u64 v[4:5], v[108:109], 0, s[34:35]
	s_brev_b32 s0, 48
	v_add_co_u32_e32 v4, vcc, s0, v4
	s_waitcnt lgkmcnt(0)
	v_add_f32_e32 v38, v38, v39
	v_addc_co_u32_e32 v5, vcc, 0, v5, vcc
	v_fmamk_f32 v38, v38, 0x3c000000, v79
	v_cmp_gt_f32_e32 vcc, s5, v38
	v_mul_f32_e32 v39, 0x4f800000, v38
	global_load_dwordx2 v[130:131], v[4:5], off
	global_load_dwordx2 v[128:129], v[4:5], off offset:64
	global_load_dwordx2 v[126:127], v[4:5], off offset:16
	global_load_dwordx2 v[124:125], v[4:5], off offset:80
	v_cndmask_b32_e32 v38, v38, v39, vcc
	v_sqrt_f32_e32 v39, v38
	global_load_dwordx2 v[122:123], v[4:5], off offset:32
	global_load_dwordx2 v[120:121], v[4:5], off offset:96
	global_load_dwordx2 v[118:119], v[4:5], off offset:48
	global_load_dwordx2 v[116:117], v[4:5], off offset:112
	v_lshl_add_u64 v[4:5], v[112:113], 2, s[60:61]
	v_add_u32_e32 v40, -1, v39
	v_fma_f32 v41, -v40, v39, v38
	v_cmp_ge_f32_e64 s[0:1], 0, v41
	v_add_u32_e32 v41, 1, v39
	global_load_dword v76, v[4:5], off
	v_cndmask_b32_e64 v40, v39, v40, s[0:1]
	v_fma_f32 v39, -v41, v39, v38
	v_cmp_lt_f32_e64 s[0:1], 0, v39
	s_nop 1
	v_cndmask_b32_e64 v39, v40, v41, s[0:1]
	v_mul_f32_e32 v40, 0x37800000, v39
	v_cndmask_b32_e32 v39, v39, v40, vcc
	v_cmp_class_f32_e32 vcc, v38, v133
	s_nop 1
	v_cndmask_b32_e32 v38, v39, v38, vcc
	v_div_scale_f32 v39, s[0:1], v38, v38, 1.0
	v_rcp_f32_e32 v40, v39
	s_mov_b64 s[0:1], 0x10000100
	v_fma_f32 v4, -v39, v40, 1.0
	v_fmac_f32_e32 v40, v4, v40
	v_div_scale_f32 v4, vcc, 1.0, v38, 1.0
	v_mul_f32_e32 v5, v4, v40
	v_fma_f32 v41, -v39, v5, v4
	v_fmac_f32_e32 v5, v41, v40
	v_fma_f32 v4, -v39, v5, v4
	v_div_fmas_f32 v4, v4, v40, v5
	v_div_fixup_f32 v4, v4, v38, 1.0
	v_mul_f32_e32 v5, v4, v6
	v_mul_f32_e32 v6, v4, v7
	v_cvt_pk_bf16_f32 v5, v5, v6
	ds_write_b16 v132, v5
	ds_write_b16_d16_hi v132, v5 offset:272
	v_mul_f32_e32 v5, v4, v8
	v_mul_f32_e32 v6, v4, v9
	v_cvt_pk_bf16_f32 v5, v5, v6
	ds_write_b16 v132, v5 offset:544
	ds_write_b16_d16_hi v132, v5 offset:816
	v_mul_f32_e32 v5, v4, v10
	v_mul_f32_e32 v6, v4, v11
	v_cvt_pk_bf16_f32 v5, v5, v6
	ds_write_b16 v132, v5 offset:1088
	ds_write_b16_d16_hi v132, v5 offset:1360
	v_mul_f32_e32 v5, v4, v12
	v_mul_f32_e32 v6, v4, v13
	v_cvt_pk_bf16_f32 v5, v5, v6
	ds_write_b16 v132, v5 offset:1632
	ds_write_b16_d16_hi v132, v5 offset:1904
	v_mul_f32_e32 v5, v4, v14
	v_mul_f32_e32 v6, v4, v15
	v_cvt_pk_bf16_f32 v5, v5, v6
	ds_write_b16 v132, v5 offset:2176
	ds_write_b16_d16_hi v132, v5 offset:2448
	v_mul_f32_e32 v5, v4, v16
	v_mul_f32_e32 v6, v4, v17
	v_cvt_pk_bf16_f32 v5, v5, v6
	ds_write_b16 v132, v5 offset:2720
	ds_write_b16_d16_hi v132, v5 offset:2992
	v_mul_f32_e32 v5, v4, v18
	v_mul_f32_e32 v6, v4, v19
	v_cvt_pk_bf16_f32 v5, v5, v6
	ds_write_b16 v132, v5 offset:3264
	ds_write_b16_d16_hi v132, v5 offset:3536
	v_mul_f32_e32 v5, v4, v20
	v_mul_f32_e32 v6, v4, v21
	v_cvt_pk_bf16_f32 v5, v5, v6
	ds_write_b16 v132, v5 offset:3808
; #define LAS __attribute__((address_space(3)))
; __device__ __forceinline__ void gmlp_phase(const Params& p, LAS unsigned char* lds, int G) {
;     ...
;                 const int gn = (g + 1) & 3, un = (g == 3) ? unit + G : unit;
;                 if (un < nunits) { const u32x4* src = (const u32x4*)(GV + (size_t)(un * 128 + j) * 512 + gn * 128 + part * 32); v0 = src[0]; v1 = src[1]; v2 = src[2]; v3 = src[3]; }
;             }
;             __syncthreads();
;             f32x16 acc0, acc1;
; #pragma unroll
;             for (int e = 0; e < 16; ++e) { acc0[e] = 0.f; acc1[e] = 0.f; }
;             const LAS bf16_t* bp0 = vT + (64 * wc + l32) * 136 + 8 * hi; const LAS bf16_t* bp1 = bp0 + 32 * 136;
; #pragma unroll
;             for (int ks = 0; ks < 8; ++ks) {
;                 const bf16x8 b0 = *(const LAS bf16x8*)(bp0 + 16 * ks), b1 = *(const LAS bf16x8*)(bp1 + 16 * ks);
;                 acc0 = __builtin_amdgcn_mfma_f32_32x32x16_bf16(b0, wf[ks], acc0, 0, 0, 0);
;                 acc1 = __builtin_amdgcn_mfma_f32_32x32x16_bf16(b1, wf[ks], acc1, 0, 0, 0);
;             }
;     ...
;                     const u32x2 gu = guv[2 * q + hb]; const f32x4 gv = *(const f32x4*)(gvn + c);
	ds_write_b16_d16_hi v132, v5 offset:4080
	v_mul_f32_e32 v5, v4, v22
	v_mul_f32_e32 v6, v4, v23
	v_cvt_pk_bf16_f32 v5, v5, v6
	ds_write_b16 v132, v5 offset:4352
	ds_write_b16_d16_hi v132, v5 offset:4624
	v_mul_f32_e32 v5, v4, v24
	v_mul_f32_e32 v6, v4, v25
	v_cvt_pk_bf16_f32 v5, v5, v6
	ds_write_b16 v132, v5 offset:4896
	ds_write_b16_d16_hi v132, v5 offset:5168
	v_mul_f32_e32 v5, v4, v26
	v_mul_f32_e32 v6, v4, v27
	v_cvt_pk_bf16_f32 v5, v5, v6
	ds_write_b16 v132, v5 offset:5440
	ds_write_b16_d16_hi v132, v5 offset:5712
	v_mul_f32_e32 v5, v4, v28
	v_mul_f32_e32 v6, v4, v29
	v_cvt_pk_bf16_f32 v5, v5, v6
	ds_write_b16 v132, v5 offset:5984
	ds_write_b16_d16_hi v132, v5 offset:6256
	v_mul_f32_e32 v5, v4, v30
	v_mul_f32_e32 v6, v4, v31
	v_cvt_pk_bf16_f32 v5, v5, v6
	ds_write_b16 v132, v5 offset:6528
	ds_write_b16_d16_hi v132, v5 offset:6800
	v_mul_f32_e32 v5, v4, v32
	v_mul_f32_e32 v6, v4, v33
	v_cvt_pk_bf16_f32 v5, v5, v6
	ds_write_b16 v132, v5 offset:7072
	ds_write_b16_d16_hi v132, v5 offset:7344
	v_mul_f32_e32 v5, v4, v36
	v_mul_f32_e32 v6, v4, v34
	v_cvt_pk_bf16_f32 v5, v5, v6
	ds_write_b16 v132, v5 offset:7616
	ds_write_b16_d16_hi v132, v5 offset:7888
	v_mul_f32_e32 v5, v4, v37
	v_mul_f32_e32 v4, v4, v35
	v_cvt_pk_bf16_f32 v4, v5, v4
	ds_write_b16 v132, v4 offset:8160
	ds_write_b16_d16_hi v132, v4 offset:8432
	v_lshl_add_u64 v[4:5], v[106:107], 0, s[34:35]
	v_lshl_add_u64 v[6:7], v[4:5], 0, s[0:1]
	s_brev_b32 s0, 8
	v_add_co_u32_e32 v4, vcc, s0, v4
	s_brev_b32 s0, 20
	s_nop 0
	v_addc_co_u32_e32 v5, vcc, 0, v5, vcc
	global_load_dwordx4 v[44:47], v[4:5], off offset:256
	global_load_dwordx4 v[32:35], v[6:7], off offset:48
	global_load_dwordx4 v[36:39], v[6:7], off offset:32
	global_load_dwordx4 v[40:43], v[6:7], off offset:16
	s_waitcnt lgkmcnt(0)
	s_barrier
	ds_read_b128 v[4:7], v134
	ds_read_b128 v[136:139], v134 offset:32
	s_waitcnt vmcnt(20) lgkmcnt(1)
	v_mfma_f32_32x32x16_bf16 v[16:31], v[4:7], v[0:3], 0
	ds_read_b128 v[4:7], v134 offset:8704
	s_waitcnt vmcnt(19) lgkmcnt(1)
	v_mfma_f32_32x32x16_bf16 v[16:31], v[136:139], v[72:75], v[16:31]
	ds_read_b128 v[136:139], v134 offset:8736
	s_waitcnt lgkmcnt(1)
	v_mfma_f32_32x32x16_bf16 v[0:15], v[4:7], v[0:3], 0
	s_waitcnt lgkmcnt(0)
	v_mfma_f32_32x32x16_bf16 v[0:15], v[136:139], v[72:75], v[0:15]
	ds_read_b128 v[72:75], v134 offset:64
	s_waitcnt vmcnt(18) lgkmcnt(0)
	v_mfma_f32_32x32x16_bf16 v[16:31], v[72:75], v[68:71], v[16:31]
	ds_read_b128 v[72:75], v134 offset:8768
	s_waitcnt lgkmcnt(0)
	v_mfma_f32_32x32x16_bf16 v[0:15], v[72:75], v[68:71], v[0:15]
	ds_read_b128 v[68:71], v134 offset:96
	global_load_dwordx4 v[72:75], v[114:115], off offset:-224
	global_load_dwordx4 v[172:175], v[114:115], off offset:-96
	global_load_dwordx4 v[176:179], v[114:115], off offset:-192
	global_load_dwordx4 v[180:183], v[114:115], off offset:-64
	global_load_dwordx4 v[184:187], v[114:115], off offset:-160
	global_load_dwordx4 v[188:191], v[114:115], off offset:-32
	global_load_dwordx4 v[192:195], v[114:115], off offset:-128
	global_load_dwordx4 v[196:199], v[114:115], off
	s_waitcnt vmcnt(25) lgkmcnt(0)
	v_mfma_f32_32x32x16_bf16 v[16:31], v[68:71], v[64:67], v[16:31]
	ds_read_b128 v[68:71], v134 offset:8800
	s_waitcnt lgkmcnt(0)
	v_mfma_f32_32x32x16_bf16 v[0:15], v[68:71], v[64:67], v[0:15]
	ds_read_b128 v[64:67], v134 offset:128
	s_waitcnt vmcnt(24) lgkmcnt(0)
	v_mfma_f32_32x32x16_bf16 v[16:31], v[64:67], v[60:63], v[16:31]
	ds_read_b128 v[64:67], v134 offset:8832
	s_waitcnt lgkmcnt(0)
	v_mfma_f32_32x32x16_bf16 v[0:15], v[64:67], v[60:63], v[0:15]
	ds_read_b128 v[60:63], v134 offset:160
	s_waitcnt vmcnt(23) lgkmcnt(0)
	v_mfma_f32_32x32x16_bf16 v[16:31], v[60:63], v[56:59], v[16:31]
	ds_read_b128 v[60:63], v134 offset:8864
	s_waitcnt lgkmcnt(0)
	v_mfma_f32_32x32x16_bf16 v[0:15], v[60:63], v[56:59], v[0:15]
	ds_read_b128 v[56:59], v134 offset:192
	s_waitcnt vmcnt(22) lgkmcnt(0)
	v_mfma_f32_32x32x16_bf16 v[16:31], v[56:59], v[52:55], v[16:31]
	ds_read_b128 v[56:59], v134 offset:8896
	s_waitcnt lgkmcnt(0)
	v_mfma_f32_32x32x16_bf16 v[0:15], v[56:59], v[52:55], v[0:15]
	ds_read_b128 v[52:55], v134 offset:224
	ds_read_b128 v[56:59], v134 offset:8928
	s_waitcnt vmcnt(21) lgkmcnt(1)
	v_mfma_f32_32x32x16_bf16 v[16:31], v[52:55], v[48:51], v[16:31]
	s_waitcnt vmcnt(20)
	v_lshlrev_b32_e32 v52, 16, v130
	s_waitcnt lgkmcnt(0)
	v_mfma_f32_32x32x16_bf16 v[0:15], v[56:59], v[48:51], v[0:15]
	s_waitcnt vmcnt(0)
; __device__ __forceinline__ unsigned cvt_pk(float lo, float hi) { unsigned r; asm volatile("v_cvt_pk_bf16_f32 %0, %1, %2" : "=v"(r) : "v"(lo), "v"(hi)); return r; }
; __device__ __forceinline__ void gmlp_phase(const Params& p, LAS unsigned char* lds, int G) {
;     ...
;             float yss = 0.f;
; #pragma unroll
;             for (int q = 0; q < 4; ++q) {
; #pragma unroll
;                 for (int hb = 0; hb < 2; ++hb) {
;                     const int c = cb + 32 * hb + 8 * q;
;                     const u32x2 gu = guv[2 * q + hb]; const f32x4 gv = *(const f32x4*)(gvn + c);
;                     const float a0 = hb ? acc1[4 * q] : acc0[4 * q], a1 = hb ? acc1[4 * q + 1] : acc0[4 * q + 1], a2 = hb ? acc1[4 * q + 2] : acc0[4 * q + 2], a3 = hb ? acc1[4 * q + 3] : acc0[4 * q + 3];
;                     const float y0 = bflo(gu.x) * (gv.x * a0 + bi), y1 = bfhi(gu.x) * (gv.y * a1 + bi), y2 = bflo(gu.y) * (gv.z * a2 + bi), y3 = bfhi(gu.y) * (gv.w * a3 + bi);
;                     yss += (y0 * y0 + y1 * y1) + (y2 * y2 + y3 * y3);
;                     u32x2 o; o.x = cvt_pk(y0, y1); o.y = cvt_pk(y2, y3);
;                     *(u32x2*)(Y + tok * 1024 + c) = o;
;                 }
;             }
;             yss += __shfl_xor(yss, 32);
;             if (hi == 0) unsafeAtomicAdd(SSA + tok, yss);
	s_nop 6
	v_fma_f32 v16, v16, v72, v76
	v_mul_f32_e32 v60, v16, v52
	v_and_b32_e32 v16, 0xffff0000, v130
	v_fma_f32 v17, v17, v73, v76
	v_mul_f32_e32 v61, v17, v16
	v_lshlrev_b32_e32 v16, 16, v131
	v_fma_f32 v17, v18, v74, v76
	v_mul_f32_e32 v62, v17, v16
	v_and_b32_e32 v16, 0xffff0000, v131
	v_fma_f32 v17, v19, v75, v76
	v_mul_f32_e32 v63, v17, v16
	v_lshl_add_u64 v[16:17], v[110:111], 0, s[34:35]
	v_add_co_u32_e32 v16, vcc, s0, v16
	v_cvt_pk_bf16_f32 v18, v60, v61
	v_cvt_pk_bf16_f32 v19, v62, v63
	v_lshlrev_b32_e32 v50, 16, v126
	s_nop 0
	v_addc_co_u32_e32 v17, vcc, 0, v17, vcc
	global_store_dwordx2 v[16:17], v[18:19], off
	s_nop 1
	v_mov_b64_e32 v[52:53], v[172:173]
	v_mov_b64_e32 v[54:55], v[174:175]
	v_lshlrev_b32_e32 v18, 16, v128
	v_and_b32_e32 v51, 0xffff0000, v126
	v_fma_f32 v0, v0, v52, v76
	v_mul_f32_e32 v18, v0, v18
	v_and_b32_e32 v0, 0xffff0000, v128
	v_fma_f32 v1, v1, v53, v76
	v_mul_f32_e32 v19, v1, v0
	v_lshlrev_b32_e32 v0, 16, v129
	v_fma_f32 v1, v2, v54, v76
	v_mul_f32_e32 v48, v1, v0
	v_and_b32_e32 v0, 0xffff0000, v129
	v_fma_f32 v1, v3, v55, v76
	v_mul_f32_e32 v49, v1, v0
	v_cvt_pk_bf16_f32 v0, v18, v19
	v_cvt_pk_bf16_f32 v1, v48, v49
	global_store_dwordx2 v[16:17], v[0:1], off offset:64
	s_nop 1
	v_mov_b64_e32 v[0:1], v[176:177]
	v_mov_b64_e32 v[2:3], v[178:179]
	v_lshlrev_b32_e32 v52, 16, v127
	v_and_b32_e32 v53, 0xffff0000, v127
	v_mul_f32_e32 v19, v19, v19
	v_mul_f32_e32 v49, v49, v49
	v_mul_f32_e32 v54, v61, v61
	v_mul_f32_e32 v55, v63, v63
	v_fmac_f32_e32 v19, v18, v18
	v_fmac_f32_e32 v49, v48, v48
	v_fmac_f32_e32 v54, v60, v60
	v_fmac_f32_e32 v55, v62, v62
	v_add_f32_e32 v18, v19, v49
	v_add_f32_e32 v54, v54, v55
	v_add_f32_e32 v18, v54, v18
	v_fma_f32 v0, v20, v0, v76
	v_fma_f32 v1, v21, v1, v76
	v_fma_f32 v2, v22, v2, v76
	v_fma_f32 v3, v23, v3, v76
	v_mul_f32_e32 v20, v0, v50
	v_mul_f32_e32 v21, v1, v51
	v_mul_f32_e32 v22, v2, v52
	v_mul_f32_e32 v23, v3, v53
	v_cvt_pk_bf16_f32 v0, v20, v21
	v_cvt_pk_bf16_f32 v1, v22, v23
	global_store_dwordx2 v[16:17], v[0:1], off offset:16
	s_nop 1
	v_mov_b64_e32 v[0:1], v[180:181]
	v_mov_b64_e32 v[2:3], v[182:183]
	v_lshlrev_b32_e32 v50, 16, v124
	v_and_b32_e32 v51, 0xffff0000, v124
	v_lshlrev_b32_e32 v52, 16, v125
	v_and_b32_e32 v53, 0xffff0000, v125
	v_mul_f32_e32 v19, v21, v21
	v_mul_f32_e32 v21, v23, v23
	v_fmac_f32_e32 v19, v20, v20
	v_fmac_f32_e32 v21, v22, v22
	v_add_f32_e32 v19, v19, v21
	v_add_f32_e32 v18, v18, v19
	v_fma_f32 v0, v4, v0, v76
	v_fma_f32 v1, v5, v1, v76
	v_fma_f32 v2, v6, v2, v76
	v_fma_f32 v3, v7, v3, v76
	v_mul_f32_e32 v4, v0, v50
	v_mul_f32_e32 v5, v1, v51
	v_mul_f32_e32 v6, v2, v52
	v_mul_f32_e32 v7, v3, v53
	v_cvt_pk_bf16_f32 v0, v4, v5
	v_cvt_pk_bf16_f32 v1, v6, v7
	global_store_dwordx2 v[16:17], v[0:1], off offset:80
	s_nop 1
	v_mov_b64_e32 v[0:1], v[184:185]
	v_mov_b64_e32 v[2:3], v[186:187]
	v_lshlrev_b32_e32 v50, 16, v122
	v_and_b32_e32 v51, 0xffff0000, v122
	v_lshlrev_b32_e32 v52, 16, v123
	v_and_b32_e32 v53, 0xffff0000, v123
	v_mul_f32_e32 v5, v5, v5
	v_mul_f32_e32 v7, v7, v7
	v_fmac_f32_e32 v5, v4, v4
	v_fmac_f32_e32 v7, v6, v6
	v_add_f32_e32 v4, v5, v7
	v_add_f32_e32 v4, v18, v4
	v_fma_f32 v0, v24, v0, v76
	v_fma_f32 v1, v25, v1, v76
	v_fma_f32 v2, v26, v2, v76
	v_fma_f32 v3, v27, v3, v76
	v_mul_f32_e32 v24, v0, v50
	v_mul_f32_e32 v25, v1, v51
	v_mul_f32_e32 v26, v2, v52
	v_mul_f32_e32 v27, v3, v53
	v_cvt_pk_bf16_f32 v0, v24, v25
	v_cvt_pk_bf16_f32 v1, v26, v27
	global_store_dwordx2 v[16:17], v[0:1], off offset:32
	s_nop 1
	v_mov_b64_e32 v[0:1], v[188:189]
	v_mov_b64_e32 v[2:3], v[190:191]
	v_lshlrev_b32_e32 v50, 16, v120
	v_and_b32_e32 v51, 0xffff0000, v120
	v_lshlrev_b32_e32 v52, 16, v121
	v_and_b32_e32 v53, 0xffff0000, v121
	v_mul_f32_e32 v5, v25, v25
	v_mul_f32_e32 v6, v27, v27
	v_fmac_f32_e32 v5, v24, v24
	v_fmac_f32_e32 v6, v26, v26
	v_add_f32_e32 v5, v5, v6
	v_add_f32_e32 v4, v4, v5
	v_fma_f32 v0, v8, v0, v76
	v_fma_f32 v1, v9, v1, v76
	v_fma_f32 v2, v10, v2, v76
	v_fma_f32 v3, v11, v3, v76
	v_mul_f32_e32 v8, v0, v50
	v_mul_f32_e32 v9, v1, v51
	v_mul_f32_e32 v10, v2, v52
	v_mul_f32_e32 v11, v3, v53
	v_cvt_pk_bf16_f32 v0, v8, v9
	v_cvt_pk_bf16_f32 v1, v10, v11
	global_store_dwordx2 v[16:17], v[0:1], off offset:96
	s_nop 1
	v_mov_b64_e32 v[0:1], v[192:193]
	v_mov_b64_e32 v[2:3], v[194:195]
	v_lshlrev_b32_e32 v50, 16, v118
	v_and_b32_e32 v51, 0xffff0000, v118
	v_lshlrev_b32_e32 v52, 16, v119
	v_and_b32_e32 v53, 0xffff0000, v119
	v_mul_f32_e32 v5, v9, v9
	v_mul_f32_e32 v6, v11, v11
	v_fmac_f32_e32 v5, v8, v8
	v_fmac_f32_e32 v6, v10, v10
	v_add_f32_e32 v5, v5, v6
	v_add_f32_e32 v4, v4, v5
	v_fma_f32 v0, v28, v0, v76
	v_fma_f32 v1, v29, v1, v76
	v_fma_f32 v2, v30, v2, v76
	v_fma_f32 v3, v31, v3, v76
	v_mul_f32_e32 v28, v0, v50
	v_mul_f32_e32 v29, v1, v51
	v_mul_f32_e32 v30, v2, v52
	v_mul_f32_e32 v31, v3, v53
	v_cvt_pk_bf16_f32 v0, v28, v29
	v_cvt_pk_bf16_f32 v1, v30, v31
	global_store_dwordx2 v[16:17], v[0:1], off offset:48
	s_nop 1
	v_mov_b64_e32 v[0:1], v[196:197]
	v_mov_b64_e32 v[2:3], v[198:199]
	v_mul_f32_e32 v5, v29, v29
	v_mul_f32_e32 v6, v31, v31
	v_fmac_f32_e32 v5, v28, v28
	v_fmac_f32_e32 v6, v30, v30
	v_and_b32_e32 v51, 0xffff0000, v116
	v_and_b32_e32 v53, 0xffff0000, v117
	v_add_f32_e32 v5, v5, v6
	v_lshlrev_b32_e32 v50, 16, v116
	v_lshlrev_b32_e32 v52, 16, v117
	v_add_f32_e32 v4, v4, v5
	v_fma_f32 v0, v12, v0, v76
	v_fma_f32 v1, v13, v1, v76
	v_fma_f32 v2, v14, v2, v76
	v_fmac_f32_e32 v76, v15, v3
	v_mul_f32_e32 v5, v1, v51
	v_mul_f32_e32 v7, v76, v53
	v_mul_f32_e32 v3, v0, v50
	v_mul_f32_e32 v6, v2, v52
	v_mul_f32_e32 v0, v5, v5
	v_mul_f32_e32 v1, v7, v7
	v_fmac_f32_e32 v0, v3, v3
	v_fmac_f32_e32 v1, v6, v6
	v_add_f32_e32 v0, v0, v1
	v_add_f32_e32 v0, v4, v0
	ds_bpermute_b32 v1, v169, v0
	v_cvt_pk_bf16_f32 v2, v3, v5
	v_cvt_pk_bf16_f32 v3, v6, v7
	global_store_dwordx2 v[16:17], v[2:3], off offset:112
	s_and_saveexec_b64 s[0:1], s[38:39]
	s_cbranch_execz .LBB0_653
	s_waitcnt lgkmcnt(0)
	v_add_f32_e32 v0, v0, v1
	global_atomic_add_f32 v[102:103], v0, off
	s_branch .LBB0_653

; #define LAS __attribute__((address_space(3)))
; __device__ __forceinline__ unsigned cvt_pk(float lo, float hi) { unsigned r; asm volatile("v_cvt_pk_bf16_f32 %0, %1, %2" : "=v"(r) : "v"(lo), "v"(hi)); return r; }
; __device__ __forceinline__ void gmlp_phase(const Params& p, LAS unsigned char* lds, int G) {
;     ...
;             for (int ks = 0; ks < 8; ++ks) {
;                 const bf16x8 b0 = *(const LAS bf16x8*)(bp0 + 16 * ks), b1 = *(const LAS bf16x8*)(bp1 + 16 * ks);
;                 acc0 = __builtin_amdgcn_mfma_f32_32x32x16_bf16(b0, wf[ks], acc0, 0, 0, 0);
;                 acc1 = __builtin_amdgcn_mfma_f32_32x32x16_bf16(b1, wf[ks], acc1, 0, 0, 0);
;             }
;             float yss = 0.f;
; #pragma unroll
;             for (int q = 0; q < 4; ++q) {
; #pragma unroll
;                 for (int hb = 0; hb < 2; ++hb) {
;                     const int c = cb + 32 * hb + 8 * q;
;                     const u32x2 gu = guv[2 * q + hb]; const f32x4 gv = *(const f32x4*)(gvn + c);
;                     const float a0 = hb ? acc1[4 * q] : acc0[4 * q], a1 = hb ? acc1[4 * q + 1] : acc0[4 * q + 1], a2 = hb ? acc1[4 * q + 2] : acc0[4 * q + 2], a3 = hb ? acc1[4 * q + 3] : acc0[4 * q + 3];
;                     const float y0 = bflo(gu.x) * (gv.x * a0 + bi), y1 = bfhi(gu.x) * (gv.y * a1 + bi), y2 = bflo(gu.y) * (gv.z * a2 + bi), y3 = bfhi(gu.y) * (gv.w * a3 + bi);
;                     yss += (y0 * y0 + y1 * y1) + (y2 * y2 + y3 * y3);
;                     u32x2 o; o.x = cvt_pk(y0, y1); o.y = cvt_pk(y2, y3);
;                     *(u32x2*)(Y + tok * 1024 + c) = o;
.LBB0_658:
	s_waitcnt lgkmcnt(0)
	s_barrier
	ds_read_b128 v[4:7], v134
	ds_read_b128 v[122:125], v134 offset:32
	s_waitcnt vmcnt(8)
	v_lshlrev_b32_e32 v101, 16, v120
	s_waitcnt lgkmcnt(1)
	v_mfma_f32_32x32x16_bf16 v[16:31], v[4:7], v[0:3], 0
	ds_read_b128 v[4:7], v134 offset:8704
	s_waitcnt lgkmcnt(1)
	v_mfma_f32_32x32x16_bf16 v[16:31], v[122:125], v[60:63], v[16:31]
	ds_read_b128 v[122:125], v134 offset:8736
	s_waitcnt lgkmcnt(1)
	v_mfma_f32_32x32x16_bf16 v[0:15], v[4:7], v[0:3], 0
	s_waitcnt lgkmcnt(0)
	v_mfma_f32_32x32x16_bf16 v[0:15], v[122:125], v[60:63], v[0:15]
	global_load_dwordx4 v[122:125], v[90:91], off offset:1536
	global_load_dwordx4 v[172:175], v[90:91], off offset:1664
	global_load_dwordx4 v[176:179], v[90:91], off offset:1568
	global_load_dwordx4 v[180:183], v[90:91], off offset:1696
	global_load_dwordx4 v[184:187], v[90:91], off offset:1600
	global_load_dwordx4 v[188:191], v[90:91], off offset:1728
	global_load_dwordx4 v[192:195], v[90:91], off offset:1632
	global_load_dwordx4 v[196:199], v[90:91], off offset:1760
	ds_read_b128 v[60:63], v134 offset:64
	s_waitcnt lgkmcnt(0)
	v_mfma_f32_32x32x16_bf16 v[16:31], v[60:63], v[72:75], v[16:31]
	ds_read_b128 v[60:63], v134 offset:8768
	s_waitcnt lgkmcnt(0)
	v_mfma_f32_32x32x16_bf16 v[0:15], v[60:63], v[72:75], v[0:15]
	ds_read_b128 v[60:63], v134 offset:96
	s_waitcnt lgkmcnt(0)
	v_mfma_f32_32x32x16_bf16 v[16:31], v[60:63], v[68:71], v[16:31]
	ds_read_b128 v[60:63], v134 offset:8800
	s_waitcnt lgkmcnt(0)
	v_mfma_f32_32x32x16_bf16 v[0:15], v[60:63], v[68:71], v[0:15]
	ds_read_b128 v[60:63], v134 offset:128
	s_waitcnt lgkmcnt(0)
	v_mfma_f32_32x32x16_bf16 v[16:31], v[60:63], v[64:67], v[16:31]
	ds_read_b128 v[60:63], v134 offset:160
	s_waitcnt lgkmcnt(0)
	v_mfma_f32_32x32x16_bf16 v[16:31], v[60:63], v[56:59], v[16:31]
	ds_read_b128 v[60:63], v134 offset:192
	s_waitcnt lgkmcnt(0)
	v_mfma_f32_32x32x16_bf16 v[16:31], v[60:63], v[52:55], v[16:31]
	ds_read_b128 v[60:63], v134 offset:224
	ds_read_b128 v[68:71], v134 offset:8832
	s_waitcnt lgkmcnt(0)
	v_mfma_f32_32x32x16_bf16 v[0:15], v[68:71], v[64:67], v[0:15]
	v_mfma_f32_32x32x16_bf16 v[16:31], v[60:63], v[48:51], v[16:31]
	v_lshlrev_b64 v[60:61], 11, v[104:105]
	v_lshl_add_u64 v[104:105], s[12:13], 0, v[60:61]
	ds_read_b128 v[60:63], v134 offset:8864
	ds_read_b128 v[72:75], v134 offset:8896
	ds_read_b128 v[126:129], v134 offset:8928
	s_waitcnt vmcnt(0)
	s_nop 5
	v_fma_f32 v16, v16, v122, v97
	s_waitcnt lgkmcnt(2)
	v_mfma_f32_32x32x16_bf16 v[0:15], v[60:63], v[56:59], v[0:15]
	v_mul_f32_e32 v64, v16, v101
	v_and_b32_e32 v16, 0xffff0000, v120
	v_fma_f32 v17, v17, v123, v97
	v_mul_f32_e32 v65, v17, v16
	v_lshlrev_b32_e32 v16, 16, v121
	v_fma_f32 v17, v18, v124, v97
	v_mul_f32_e32 v66, v17, v16
	v_and_b32_e32 v16, 0xffff0000, v121
	v_fma_f32 v17, v19, v125, v97
	v_mul_f32_e32 v56, v17, v16
	v_lshl_add_u64 v[16:17], v[104:105], 0, v[76:77]
	v_cvt_pk_bf16_f32 v18, v64, v65
	v_cvt_pk_bf16_f32 v19, v66, v56
	global_store_dwordx2 v[16:17], v[18:19], off offset:768
	s_waitcnt lgkmcnt(1)
	v_mfma_f32_32x32x16_bf16 v[0:15], v[72:75], v[52:55], v[0:15]
	s_nop 1
	v_mov_b64_e32 v[52:53], v[172:173]
	v_mov_b64_e32 v[54:55], v[174:175]
	v_lshlrev_b32_e32 v18, 16, v118
	v_and_b32_e32 v19, 0xffff0000, v118
	v_lshlrev_b32_e32 v57, 16, v119
	v_and_b32_e32 v58, 0xffff0000, v119
	s_waitcnt lgkmcnt(0)
; __device__ __forceinline__ unsigned cvt_pk(float lo, float hi) { unsigned r; asm volatile("v_cvt_pk_bf16_f32 %0, %1, %2" : "=v"(r) : "v"(lo), "v"(hi)); return r; }
; __device__ __forceinline__ void gmlp_phase(const Params& p, LAS unsigned char* lds, int G) {
;     ...
;             float yss = 0.f;
; #pragma unroll
;             for (int q = 0; q < 4; ++q) {
; #pragma unroll
;                 for (int hb = 0; hb < 2; ++hb) {
;                     const int c = cb + 32 * hb + 8 * q;
;                     const u32x2 gu = guv[2 * q + hb]; const f32x4 gv = *(const f32x4*)(gvn + c);
;                     const float a0 = hb ? acc1[4 * q] : acc0[4 * q], a1 = hb ? acc1[4 * q + 1] : acc0[4 * q + 1], a2 = hb ? acc1[4 * q + 2] : acc0[4 * q + 2], a3 = hb ? acc1[4 * q + 3] : acc0[4 * q + 3];
;                     const float y0 = bflo(gu.x) * (gv.x * a0 + bi), y1 = bfhi(gu.x) * (gv.y * a1 + bi), y2 = bflo(gu.y) * (gv.z * a2 + bi), y3 = bfhi(gu.y) * (gv.w * a3 + bi);
;                     yss += (y0 * y0 + y1 * y1) + (y2 * y2 + y3 * y3);
;                     u32x2 o; o.x = cvt_pk(y0, y1); o.y = cvt_pk(y2, y3);
;                     *(u32x2*)(Y + tok * 1024 + c) = o;
;                 }
;             }
;             yss += __shfl_xor(yss, 32);
;             if (hi == 0) unsafeAtomicAdd(SSA + tok, yss);
	v_mfma_f32_32x32x16_bf16 v[0:15], v[126:129], v[48:51], v[0:15]
	v_lshlrev_b32_e32 v50, 16, v116
	v_and_b32_e32 v51, 0xffff0000, v116
	s_nop 8
	v_fma_f32 v0, v0, v52, v97
	v_fma_f32 v1, v1, v53, v97
	v_fma_f32 v2, v2, v54, v97
	v_fma_f32 v3, v3, v55, v97
	v_mul_f32_e32 v18, v0, v18
	v_mul_f32_e32 v19, v1, v19
	v_mul_f32_e32 v48, v2, v57
	v_mul_f32_e32 v49, v3, v58
	v_cvt_pk_bf16_f32 v0, v18, v19
	v_cvt_pk_bf16_f32 v1, v48, v49
	global_store_dwordx2 v[16:17], v[0:1], off offset:832
	s_nop 1
	v_mov_b64_e32 v[0:1], v[176:177]
	v_mov_b64_e32 v[2:3], v[178:179]
	v_lshlrev_b32_e32 v52, 16, v117
	v_and_b32_e32 v53, 0xffff0000, v117
	v_mul_f32_e32 v19, v19, v19
	v_mul_f32_e32 v49, v49, v49
	v_mul_f32_e32 v54, v65, v65
	v_mul_f32_e32 v55, v56, v56
	v_fmac_f32_e32 v19, v18, v18
	v_fmac_f32_e32 v49, v48, v48
	v_fmac_f32_e32 v54, v64, v64
	v_fmac_f32_e32 v55, v66, v66
	v_add_f32_e32 v18, v19, v49
	v_add_f32_e32 v54, v54, v55
	v_add_f32_e32 v18, v54, v18
	v_fma_f32 v0, v20, v0, v97
	v_fma_f32 v1, v21, v1, v97
	v_fma_f32 v2, v22, v2, v97
	v_fma_f32 v3, v23, v3, v97
	v_mul_f32_e32 v20, v0, v50
	v_mul_f32_e32 v21, v1, v51
	v_mul_f32_e32 v22, v2, v52
	v_mul_f32_e32 v23, v3, v53
	v_cvt_pk_bf16_f32 v0, v20, v21
	v_cvt_pk_bf16_f32 v1, v22, v23
	global_store_dwordx2 v[16:17], v[0:1], off offset:784
	s_nop 1
	v_mov_b64_e32 v[0:1], v[180:181]
	v_mov_b64_e32 v[2:3], v[182:183]
	v_lshlrev_b32_e32 v50, 16, v114
	v_and_b32_e32 v51, 0xffff0000, v114
	v_lshlrev_b32_e32 v52, 16, v115
	v_and_b32_e32 v53, 0xffff0000, v115
	v_mul_f32_e32 v19, v21, v21
	v_mul_f32_e32 v21, v23, v23
	v_fmac_f32_e32 v19, v20, v20
	v_fmac_f32_e32 v21, v22, v22
	v_add_f32_e32 v19, v19, v21
	v_add_f32_e32 v18, v18, v19
	v_fma_f32 v0, v4, v0, v97
	v_fma_f32 v1, v5, v1, v97
	v_fma_f32 v2, v6, v2, v97
	v_fma_f32 v3, v7, v3, v97
	v_mul_f32_e32 v4, v0, v50
	v_mul_f32_e32 v5, v1, v51
	v_mul_f32_e32 v6, v2, v52
	v_mul_f32_e32 v7, v3, v53
	v_cvt_pk_bf16_f32 v0, v4, v5
	v_cvt_pk_bf16_f32 v1, v6, v7
	global_store_dwordx2 v[16:17], v[0:1], off offset:848
	s_nop 1
	v_mov_b64_e32 v[0:1], v[184:185]
	v_mov_b64_e32 v[2:3], v[186:187]
	v_lshlrev_b32_e32 v50, 16, v112
	v_and_b32_e32 v51, 0xffff0000, v112
	v_lshlrev_b32_e32 v52, 16, v113
	v_and_b32_e32 v53, 0xffff0000, v113
	v_mul_f32_e32 v5, v5, v5
	v_mul_f32_e32 v7, v7, v7
	v_fmac_f32_e32 v5, v4, v4
	v_fmac_f32_e32 v7, v6, v6
	v_add_f32_e32 v4, v5, v7
	v_add_f32_e32 v4, v18, v4
	v_fma_f32 v0, v24, v0, v97
	v_fma_f32 v1, v25, v1, v97
	v_fma_f32 v2, v26, v2, v97
	v_fma_f32 v3, v27, v3, v97
	v_mul_f32_e32 v24, v0, v50
	v_mul_f32_e32 v25, v1, v51
	v_mul_f32_e32 v26, v2, v52
	v_mul_f32_e32 v27, v3, v53
	v_cvt_pk_bf16_f32 v0, v24, v25
	v_cvt_pk_bf16_f32 v1, v26, v27
	global_store_dwordx2 v[16:17], v[0:1], off offset:800
	s_nop 1
	v_mov_b64_e32 v[0:1], v[188:189]
	v_mov_b64_e32 v[2:3], v[190:191]
	v_lshlrev_b32_e32 v50, 16, v110
	v_and_b32_e32 v51, 0xffff0000, v110
	v_lshlrev_b32_e32 v52, 16, v111
	v_and_b32_e32 v53, 0xffff0000, v111
	v_mul_f32_e32 v5, v25, v25
	v_mul_f32_e32 v6, v27, v27
	v_fmac_f32_e32 v5, v24, v24
	v_fmac_f32_e32 v6, v26, v26
	v_add_f32_e32 v5, v5, v6
	v_add_f32_e32 v4, v4, v5
	v_fma_f32 v0, v8, v0, v97
	v_fma_f32 v1, v9, v1, v97
	v_fma_f32 v2, v10, v2, v97
	v_fma_f32 v3, v11, v3, v97
	v_mul_f32_e32 v8, v0, v50
	v_mul_f32_e32 v9, v1, v51
	v_mul_f32_e32 v10, v2, v52
	v_mul_f32_e32 v11, v3, v53
	v_cvt_pk_bf16_f32 v0, v8, v9
	v_cvt_pk_bf16_f32 v1, v10, v11
	global_store_dwordx2 v[16:17], v[0:1], off offset:864
	s_nop 1
	v_mov_b64_e32 v[0:1], v[192:193]
	v_mov_b64_e32 v[2:3], v[194:195]
	v_lshlrev_b32_e32 v50, 16, v108
	v_and_b32_e32 v51, 0xffff0000, v108
	v_lshlrev_b32_e32 v52, 16, v109
	v_and_b32_e32 v53, 0xffff0000, v109
	v_mul_f32_e32 v5, v9, v9
	v_mul_f32_e32 v6, v11, v11
	v_fmac_f32_e32 v5, v8, v8
	v_fmac_f32_e32 v6, v10, v10
	v_add_f32_e32 v5, v5, v6
	v_add_f32_e32 v4, v4, v5
	v_fma_f32 v0, v28, v0, v97
	v_fma_f32 v1, v29, v1, v97
	v_fma_f32 v2, v30, v2, v97
	v_fma_f32 v3, v31, v3, v97
	v_mul_f32_e32 v28, v0, v50
	v_mul_f32_e32 v29, v1, v51
	v_mul_f32_e32 v30, v2, v52
	v_mul_f32_e32 v31, v3, v53
	v_cvt_pk_bf16_f32 v0, v28, v29
	v_cvt_pk_bf16_f32 v1, v30, v31
	global_store_dwordx2 v[16:17], v[0:1], off offset:816
	s_nop 1
	v_mov_b64_e32 v[0:1], v[196:197]
	v_mov_b64_e32 v[2:3], v[198:199]
	v_mul_f32_e32 v5, v29, v29
	v_mul_f32_e32 v6, v31, v31
	v_fmac_f32_e32 v5, v28, v28
	v_fmac_f32_e32 v6, v30, v30
	v_and_b32_e32 v51, 0xffff0000, v106
	v_and_b32_e32 v53, 0xffff0000, v107
	v_add_f32_e32 v5, v5, v6
	v_lshlrev_b32_e32 v50, 16, v106
	v_lshlrev_b32_e32 v52, 16, v107
	v_add_f32_e32 v4, v4, v5
	v_fma_f32 v0, v12, v0, v97
	v_fma_f32 v1, v13, v1, v97
	v_fma_f32 v2, v14, v2, v97
	v_fmac_f32_e32 v97, v15, v3
	v_mul_f32_e32 v5, v1, v51
	v_mul_f32_e32 v7, v97, v53
	v_mul_f32_e32 v3, v0, v50
	v_mul_f32_e32 v6, v2, v52
	v_mul_f32_e32 v0, v5, v5
	v_mul_f32_e32 v1, v7, v7
	v_fmac_f32_e32 v0, v3, v3
	v_fmac_f32_e32 v1, v6, v6
	v_add_f32_e32 v0, v0, v1
	v_add_f32_e32 v0, v4, v0
	ds_bpermute_b32 v1, v169, v0
	v_cvt_pk_bf16_f32 v2, v3, v5
	v_cvt_pk_bf16_f32 v3, v6, v7
	global_store_dwordx2 v[16:17], v[2:3], off offset:880
	s_and_saveexec_b64 s[34:35], s[38:39]
	s_cbranch_execz .LBB0_651
	s_waitcnt lgkmcnt(0)
	v_add_f32_e32 v0, v0, v1
	global_atomic_add_f32 v[102:103], v0, off
	s_branch .LBB0_651
